# hand-written software-pipelined weight conversion (P0 layer 0, w_in tail layer 1) + first barrier's invalidate on wave 1
# speedup vs baseline: 1.0540x; 1.0096x over previous
.LBB0_70:
	s_andn2_b64 vcc, exec, s[0:1]
	s_cbranch_vccnz .LBB0_104
	s_add_i32 s2, s58, 0xfffffe80
	s_cmpk_lt_u32 s2, 0xbc0
	s_cbranch_scc1 .LBB0_10
	s_cmpk_gt_u32 s2, 0x27f
	s_mov_b64 s[0:1], -1
	s_cbranch_scc0 .LBB0_101
	s_cmpk_gt_u32 s2, 0x37f
	s_cbranch_scc0 .LBB0_98
	s_cmpk_gt_u32 s2, 0x8ff
	s_cbranch_scc0 .LBB0_87
	s_cmpk_gt_u32 s2, 0xbbf
	s_cbranch_scc0 .LBB0_84
	s_cmpk_gt_u32 s2, 0xbcb
	s_cbranch_scc0 .LBB0_81
	s_cmpk_gt_u32 s2, 0xbd7
	s_cbranch_scc0 .LBB0_78
	s_add_i32 s0, s58, 0xfffff2a8
	s_cmp_gt_u32 s0, 5
	s_cselect_b32 s4, 64, 0
	s_lshl_b32 s1, s0, 6
	s_add_i32 s5, s1, 0x3ffe80
	s_cmp_lt_u32 s0, 6
	s_cselect_b32 s0, s1, s5
	s_and_b32 s5, s0, 0x3fffc0
	v_mov_b32_e32 v20, v137
	s_lshl_b32 s0, s5, 2
	v_readlane_b32 s8, v242, 26
	v_readlane_b32 s9, v242, 27
	v_ashrrev_i32_e32 v21, 6, v20
	s_add_u32 s0, s8, s0
	v_lshlrev_b32_e32 v2, 2, v20
	s_addc_u32 s1, s9, 0
	v_and_b32_e32 v80, 0xfc, v2
	v_add_u32_e32 v22, s4, v21
	v_lshl_add_u64 v[2:3], s[0:1], 0, v[80:81]
	s_movk_i32 s6, 0x600
	v_add_u32_e32 v6, 4, v22
	v_add_u32_e32 v8, 8, v22
	v_add_u32_e32 v10, 12, v22
	v_add_u32_e32 v12, 16, v22
	v_add_u32_e32 v14, 20, v22
	v_add_u32_e32 v16, 24, v22
	v_add_u32_e32 v18, 28, v22
	v_mad_i64_i32 v[4:5], s[0:1], v22, s6, v[2:3]
	v_mad_i64_i32 v[6:7], s[0:1], v6, s6, v[2:3]
	v_mad_i64_i32 v[8:9], s[0:1], v8, s6, v[2:3]
	v_mad_i64_i32 v[10:11], s[0:1], v10, s6, v[2:3]
	v_mad_i64_i32 v[12:13], s[0:1], v12, s6, v[2:3]
	v_mad_i64_i32 v[14:15], s[0:1], v14, s6, v[2:3]
	v_mad_i64_i32 v[16:17], s[0:1], v16, s6, v[2:3]
	v_mad_i64_i32 v[18:19], s[0:1], v18, s6, v[2:3]
	global_load_dword v23, v[4:5], off
	global_load_dword v24, v[6:7], off
	global_load_dword v25, v[8:9], off
	global_load_dword v26, v[10:11], off
	global_load_dword v27, v[12:13], off
	global_load_dword v28, v[14:15], off
	global_load_dword v29, v[16:17], off
	s_nop 0
	global_load_dword v18, v[18:19], off
	v_add_u32_e32 v4, 32, v22
	v_add_u32_e32 v6, 36, v22
	v_add_u32_e32 v8, 40, v22
	v_add_u32_e32 v10, 44, v22
	v_add_u32_e32 v12, 48, v22
	v_add_u32_e32 v14, 52, v22
	v_add_u32_e32 v16, 56, v22
	v_add_u32_e32 v19, 60, v22
	v_mad_i64_i32 v[4:5], s[0:1], v4, s6, v[2:3]
	v_mad_i64_i32 v[6:7], s[0:1], v6, s6, v[2:3]
	v_mad_i64_i32 v[8:9], s[0:1], v8, s6, v[2:3]
	v_mad_i64_i32 v[10:11], s[0:1], v10, s6, v[2:3]
	v_mad_i64_i32 v[12:13], s[0:1], v12, s6, v[2:3]
	v_mad_i64_i32 v[14:15], s[0:1], v14, s6, v[2:3]
	v_mad_i64_i32 v[16:17], s[0:1], v16, s6, v[2:3]
	v_mad_i64_i32 v[2:3], s[0:1], v19, s6, v[2:3]
	global_load_dword v4, v[4:5], off
	s_nop 0
	global_load_dword v5, v[6:7], off
	s_nop 0
	global_load_dword v6, v[8:9], off
	global_load_dword v7, v[10:11], off
	s_nop 0
	global_load_dword v8, v[12:13], off
	global_load_dword v9, v[14:15], off
	global_load_dword v10, v[16:17], off
	s_nop 0
	global_load_dword v2, v[2:3], off
	s_movk_i32 s0, 0x104
	v_mul_lo_u32 v3, v21, s0
	v_add3_u32 v3, 0, v80, v3
	v_ashrrev_i32_e32 v13, 3, v20
	v_readlane_b32 s6, v242, 46
	v_readlane_b32 s7, v242, 47
	v_readlane_b32 s10, v242, 28
	v_readlane_b32 s11, v242, 29
	v_readlane_b32 s12, v242, 30
	v_readlane_b32 s13, v242, 31
	v_readlane_b32 s14, v242, 32
	v_readlane_b32 s15, v242, 33
	v_readlane_b32 s16, v242, 34
	v_readlane_b32 s17, v242, 35
	v_readlane_b32 s18, v242, 36
	v_readlane_b32 s19, v242, 37
	v_readlane_b32 s20, v242, 38
	v_readlane_b32 s21, v242, 39
	v_readlane_b32 s22, v242, 40
	v_readlane_b32 s23, v242, 41
	s_waitcnt vmcnt(15)
	ds_write_b32 v3, v23
	s_waitcnt vmcnt(14)
	ds_write_b32 v3, v24 offset:1040
	s_waitcnt vmcnt(13)
	ds_write_b32 v3, v25 offset:2080
	s_waitcnt vmcnt(12)
	ds_write_b32 v3, v26 offset:3120
	s_waitcnt vmcnt(11)
	ds_write_b32 v3, v27 offset:4160
	s_waitcnt vmcnt(10)
	ds_write_b32 v3, v28 offset:5200
	s_waitcnt vmcnt(9)
	ds_write_b32 v3, v29 offset:6240
	s_waitcnt vmcnt(8)
	ds_write_b32 v3, v18 offset:7280
	s_waitcnt vmcnt(7)
	ds_write_b32 v3, v4 offset:8320
	s_waitcnt vmcnt(6)
	ds_write_b32 v3, v5 offset:9360
	s_waitcnt vmcnt(5)
	ds_write_b32 v3, v6 offset:10400
	s_waitcnt vmcnt(4)
	ds_write_b32 v3, v7 offset:11440
	s_waitcnt vmcnt(3)
	ds_write_b32 v3, v8 offset:12480
	s_waitcnt vmcnt(2)
	ds_write_b32 v3, v9 offset:13520
	s_waitcnt vmcnt(1)
	ds_write_b32 v3, v10 offset:14560
	s_waitcnt vmcnt(0)
	ds_write_b32 v3, v2 offset:15600
	v_lshlrev_b32_e32 v2, 3, v20
	v_and_b32_e32 v2, 56, v2
	v_mad_u32_u24 v12, v2, s0, 0
	v_lshl_add_u32 v6, v13, 2, v12
	s_waitcnt lgkmcnt(0)
	s_barrier
	v_lshlrev_b32_e32 v80, 1, v2
	ds_read2_b32 v[2:3], v6 offset1:65
	ds_read2_b32 v[4:5], v6 offset0:130 offset1:195
	v_add_u32_e32 v8, 0x400, v6
	ds_read2_b32 v[6:7], v8 offset0:4 offset1:69
	ds_read2_b32 v[8:9], v8 offset0:134 offset1:199
	s_lshl_b32 s0, s4, 1
	s_add_u32 s0, s6, s0
	s_waitcnt lgkmcnt(3)
	v_cvt_pk_bf16_f32 v2, v2, v3
	s_waitcnt lgkmcnt(2)
	v_cvt_pk_bf16_f32 v3, v4, v5
	s_waitcnt lgkmcnt(1)
	v_cvt_pk_bf16_f32 v4, v6, v7
	v_add_u32_e32 v6, s5, v13
	s_addc_u32 s1, s7, 0
	v_ashrrev_i32_e32 v7, 31, v6
	v_lshl_add_u64 v[10:11], s[0:1], 0, v[80:81]
	v_lshlrev_b64 v[6:7], 8, v[6:7]
	s_waitcnt lgkmcnt(0)
	v_cvt_pk_bf16_f32 v5, v8, v9
	v_lshl_add_u64 v[6:7], v[10:11], 0, v[6:7]
	global_store_dwordx4 v[6:7], v[2:5], off
	s_mov_b64 s[0:1], 0
	s_nop 0
	v_add_u32_e32 v2, 0x100, v20
	v_ashrrev_i32_e32 v4, 3, v2
	v_lshl_add_u32 v5, v4, 2, v12
	v_add_u32_e32 v6, 0x400, v5
	ds_read2_b32 v[2:3], v6 offset0:134 offset1:199
	ds_read2_b32 v[6:7], v6 offset0:4 offset1:69
	ds_read2_b32 v[8:9], v5 offset0:130 offset1:195
	ds_read2_b32 v[12:13], v5 offset1:65
	v_add_u32_e32 v14, s5, v4
	v_ashrrev_i32_e32 v15, 31, v14
	s_waitcnt lgkmcnt(2)
	v_cvt_pk_bf16_f32 v4, v6, v7
	v_lshlrev_b64 v[6:7], 8, v[14:15]
	v_cvt_pk_bf16_f32 v5, v2, v3
	s_waitcnt lgkmcnt(1)
	v_cvt_pk_bf16_f32 v3, v8, v9
	s_waitcnt lgkmcnt(0)
	v_cvt_pk_bf16_f32 v2, v12, v13
	v_lshl_add_u64 v[6:7], v[10:11], 0, v[6:7]
	global_store_dwordx4 v[6:7], v[2:5], off
	s_barrier

.LBB0_149:
	v_readlane_b32 s100, v242, 0
	s_nop 0
	s_cmpk_ge_u32 s100, 0x180
	s_cbranch_scc1 .Lwc0_ng
	s_add_u32 s100, s100, 0x600
	s_movk_i32 s41, 0x180
	s_movk_i32 s44, 0xbc0
	s_branch .Lwc0_set
.Lwc0_ng:
	s_sub_u32 s100, s100, 0x180
	s_movk_i32 s41, 0x80
	s_movk_i32 s44, 0x600
.Lwc0_set:
	v_writelane_b32 v207, s41, 0
	v_writelane_b32 v207, s44, 1
	s_waitcnt vmcnt(0) lgkmcnt(0)
	s_barrier
	v_readlane_b32 s0, v242, 42
	v_readlane_b32 s1, v242, 43
	v_readlane_b32 s4, v242, 3
	v_readlane_b32 s5, v242, 4
	v_lshrrev_b32_e32 v203, 6, v137
	v_and_b32_e32 v204, 63, v137
	s_sub_u32 s0, s0, 0x118
	s_subb_u32 s1, s1, 0
	v_lshrrev_b32_e32 v205, 3, v137
	v_and_b32_e32 v206, 7, v137
	v_mul_u32_u24_e32 v194, 65, v203
	v_mul_u32_u24_e32 v195, 0x208, v206
	v_add_u32_e32 v194, v194, v204
	v_add_u32_e32 v195, v195, v205
	v_lshlrev_b32_e32 v194, 2, v194
	v_lshlrev_b32_e32 v195, 2, v195
	v_lshlrev_b32_e32 v204, 2, v204
	v_lshlrev_b32_e32 v206, 4, v206
	v_add_u32_e32 v196, 0x400, v195
	v_add_u32_e32 v197, 0x80, v195
	v_add_u32_e32 v198, 0x480, v195
	v_readlane_b32 s41, v207, 1
	s_nop 0
	s_cmp_ge_u32 s100, s41
	s_cbranch_scc1 .Lwc0_done
	s_mov_b32 s101, s100
	s_cmpk_ge_u32 s101, 0x900
	s_cbranch_scc1 .Lwc0_t3_1
	s_cmpk_ge_u32 s101, 0x380
	s_cbranch_scc1 .Lwc0_t2_1
	s_cmpk_ge_u32 s101, 0x280
	s_cbranch_scc1 .Lwc0_t1_1
	s_movk_i32 s41, 0x78
	s_sub_u32 s99, s101, 0
	s_mul_i32 s44, s99, 0x66667
	s_lshr_b32 s44, s44, 24
	s_mul_i32 s36, s44, 40
	s_sub_u32 s99, s99, s36
	s_mul_i32 s38, s44, 0xa0000
	s_lshl_b32 s36, s99, 8
	s_add_u32 s38, s38, s36
	s_add_u32 s38, s38, 0x0
	s_lshl_b32 s36, s99, 6
	s_mov_b32 s32, 0x10000
	s_mul_i32 s36, s36, 0x800
	s_lshl_b32 s44, s44, 7
	s_add_u32 s36, s36, s44
	s_add_u32 s36, s36, 0x0
	s_mov_b32 s37, 0xa000
	s_movk_i32 s44, 0x800
	s_mov_b32 s99, 0x2800
	s_branch .Lwc0_tj_1
.Lwc0_t1_1:
	s_movk_i32 s41, 0x80
	s_sub_u32 s99, s101, 640
	s_mul_i32 s44, s99, 0x100000
	s_lshr_b32 s44, s44, 24
	s_mul_i32 s36, s44, 16
	s_sub_u32 s99, s99, s36
	s_mul_i32 s38, s44, 0x40000
	s_lshl_b32 s36, s99, 8
	s_add_u32 s38, s38, s36
	s_add_u32 s38, s38, 0x0
	s_lshl_b32 s36, s99, 6
	s_mov_b32 s32, 0x10000
	s_mul_i32 s36, s36, 0x800
	s_lshl_b32 s44, s44, 7
	s_add_u32 s36, s36, s44
	s_add_u32 s36, s36, 0xa00000
	s_mov_b32 s37, 0x4000
	s_movk_i32 s44, 0x800
	s_mov_b32 s99, 0x1000
	s_branch .Lwc0_tj_1
.Lwc0_t2_1:
	s_movk_i32 s41, 0xf0
	s_sub_u32 s99, s101, 896
	s_mul_i32 s44, s99, 0x2e8bb
	s_lshr_b32 s44, s44, 24
	s_mul_i32 s36, s44, 88
	s_sub_u32 s99, s99, s36
	s_mul_i32 s38, s44, 0x160000
	s_lshl_b32 s36, s99, 8
	s_add_u32 s38, s38, s36
	s_add_u32 s38, s38, 0x0
	s_cmpk_ge_u32 s99, 44
	s_cselect_b32 s36, 44, 0
	s_cselect_b32 s37, 32, 0
	s_sub_u32 s36, s99, s36
	s_lshl_b32 s36, s36, 7
	s_add_u32 s36, s36, s37
	s_mov_b32 s32, 0x20000
	s_mul_i32 s36, s36, 0x800
	s_lshl_b32 s44, s44, 7
	s_add_u32 s36, s36, s44
	s_add_u32 s36, s36, 0xe00000
	s_mov_b32 s37, 0x16000
	s_movk_i32 s44, 0x800
	s_mov_b32 s99, 0x5800
	s_branch .Lwc0_tj_1
.Lwc0_t3_1:
	s_movk_i32 s41, 0xf8
	s_sub_u32 s99, s101, 2304
	s_mul_i32 s44, s99, 0x100000
	s_lshr_b32 s44, s44, 24
	s_mul_i32 s36, s44, 16
	s_sub_u32 s99, s99, s36
	s_mul_i32 s38, s44, 0x40000
	s_lshl_b32 s36, s99, 8
	s_add_u32 s38, s38, s36
	s_add_u32 s38, s38, 0x0
	s_lshl_b32 s36, s99, 6
	s_mov_b32 s32, 0x2c000
	s_mul_i32 s36, s36, 0x1600
	s_lshl_b32 s44, s44, 7
	s_add_u32 s36, s36, s44
	s_add_u32 s36, s36, 0x2400000
	s_mov_b32 s37, 0x4000
	s_movk_i32 s44, 0x1600
	s_mov_b32 s99, 0x1000
.Lwc0_tj_1:
	s_load_dwordx2 s[2:3], s[0:1], s41
	s_add_u32 s52, s4, s36
	s_addc_u32 s53, s5, 0
	v_mad_u32_u24 v199, v203, s99, v204
	v_mad_u32_u24 v201, v205, s44, v206
	s_waitcnt lgkmcnt(0)
	s_add_u32 s38, s2, s38
	s_addc_u32 s39, s3, 0
	global_load_dword v138, v199, s[38:39]
	s_add_u32 s38, s38, s37
	s_addc_u32 s39, s39, 0
	global_load_dword v139, v199, s[38:39]
	s_add_u32 s38, s38, s37
	s_addc_u32 s39, s39, 0
	global_load_dword v140, v199, s[38:39]
	s_add_u32 s38, s38, s37
	s_addc_u32 s39, s39, 0
	global_load_dword v141, v199, s[38:39]
	s_add_u32 s38, s38, s37
	s_addc_u32 s39, s39, 0
	global_load_dword v142, v199, s[38:39]
	s_add_u32 s38, s38, s37
	s_addc_u32 s39, s39, 0
	global_load_dword v143, v199, s[38:39]
	s_add_u32 s38, s38, s37
	s_addc_u32 s39, s39, 0
	global_load_dword v144, v199, s[38:39]
	s_add_u32 s38, s38, s37
	s_addc_u32 s39, s39, 0
	global_load_dword v145, v199, s[38:39]
	s_add_u32 s38, s38, s37
	s_addc_u32 s39, s39, 0
	global_load_dword v146, v199, s[38:39]
	s_add_u32 s38, s38, s37
	s_addc_u32 s39, s39, 0
	global_load_dword v147, v199, s[38:39]
	s_add_u32 s38, s38, s37
	s_addc_u32 s39, s39, 0
	global_load_dword v148, v199, s[38:39]
	s_add_u32 s38, s38, s37
	s_addc_u32 s39, s39, 0
	global_load_dword v149, v199, s[38:39]
	s_add_u32 s38, s38, s37
	s_addc_u32 s39, s39, 0
	global_load_dword v150, v199, s[38:39]
	s_add_u32 s38, s38, s37
	s_addc_u32 s39, s39, 0
	global_load_dword v151, v199, s[38:39]
	s_add_u32 s38, s38, s37
	s_addc_u32 s39, s39, 0
	global_load_dword v152, v199, s[38:39]
	s_add_u32 s38, s38, s37
	s_addc_u32 s39, s39, 0
	global_load_dword v153, v199, s[38:39]
.Lwc0_loop:
	v_readlane_b32 s41, v207, 0
	v_readlane_b32 s44, v207, 1
	s_nop 0
	s_add_u32 s100, s100, s41
	s_cmp_ge_u32 s100, s44
	s_cbranch_scc1 .Lwc0_last0
	s_mov_b32 s101, s100
	s_cmpk_ge_u32 s101, 0x900
	s_cbranch_scc1 .Lwc0_t3_2
	s_cmpk_ge_u32 s101, 0x380
	s_cbranch_scc1 .Lwc0_t2_2
	s_cmpk_ge_u32 s101, 0x280
	s_cbranch_scc1 .Lwc0_t1_2
	s_movk_i32 s41, 0x78
	s_sub_u32 s99, s101, 0
	s_mul_i32 s44, s99, 0x66667
	s_lshr_b32 s44, s44, 24
	s_mul_i32 s36, s44, 40
	s_sub_u32 s99, s99, s36
	s_mul_i32 s38, s44, 0xa0000
	s_lshl_b32 s36, s99, 8
	s_add_u32 s38, s38, s36
	s_add_u32 s38, s38, 0x0
	s_lshl_b32 s36, s99, 6
	s_mov_b32 s35, 0x10000
	s_mul_i32 s36, s36, 0x800
	s_lshl_b32 s44, s44, 7
	s_add_u32 s36, s36, s44
	s_add_u32 s36, s36, 0x0
	s_mov_b32 s37, 0xa000
	s_movk_i32 s44, 0x800
	s_mov_b32 s99, 0x2800
	s_branch .Lwc0_tj_2
.Lwc0_t1_2:
	s_movk_i32 s41, 0x80
	s_sub_u32 s99, s101, 640
	s_mul_i32 s44, s99, 0x100000
	s_lshr_b32 s44, s44, 24
	s_mul_i32 s36, s44, 16
	s_sub_u32 s99, s99, s36
	s_mul_i32 s38, s44, 0x40000
	s_lshl_b32 s36, s99, 8
	s_add_u32 s38, s38, s36
	s_add_u32 s38, s38, 0x0
	s_lshl_b32 s36, s99, 6
	s_mov_b32 s35, 0x10000
	s_mul_i32 s36, s36, 0x800
	s_lshl_b32 s44, s44, 7
	s_add_u32 s36, s36, s44
	s_add_u32 s36, s36, 0xa00000
	s_mov_b32 s37, 0x4000
	s_movk_i32 s44, 0x800
	s_mov_b32 s99, 0x1000
	s_branch .Lwc0_tj_2
.Lwc0_t2_2:
	s_movk_i32 s41, 0xf0
	s_sub_u32 s99, s101, 896
	s_mul_i32 s44, s99, 0x2e8bb
	s_lshr_b32 s44, s44, 24
	s_mul_i32 s36, s44, 88
	s_sub_u32 s99, s99, s36
	s_mul_i32 s38, s44, 0x160000
	s_lshl_b32 s36, s99, 8
	s_add_u32 s38, s38, s36
	s_add_u32 s38, s38, 0x0
	s_cmpk_ge_u32 s99, 44
	s_cselect_b32 s36, 44, 0
	s_cselect_b32 s37, 32, 0
	s_sub_u32 s36, s99, s36
	s_lshl_b32 s36, s36, 7
	s_add_u32 s36, s36, s37
	s_mov_b32 s35, 0x20000
	s_mul_i32 s36, s36, 0x800
	s_lshl_b32 s44, s44, 7
	s_add_u32 s36, s36, s44
	s_add_u32 s36, s36, 0xe00000
	s_mov_b32 s37, 0x16000
	s_movk_i32 s44, 0x800
	s_mov_b32 s99, 0x5800
	s_branch .Lwc0_tj_2
.Lwc0_t3_2:
	s_movk_i32 s41, 0xf8
	s_sub_u32 s99, s101, 2304
	s_mul_i32 s44, s99, 0x100000
	s_lshr_b32 s44, s44, 24
	s_mul_i32 s36, s44, 16
	s_sub_u32 s99, s99, s36
	s_mul_i32 s38, s44, 0x40000
	s_lshl_b32 s36, s99, 8
	s_add_u32 s38, s38, s36
	s_add_u32 s38, s38, 0x0
	s_lshl_b32 s36, s99, 6
	s_mov_b32 s35, 0x2c000
	s_mul_i32 s36, s36, 0x1600
	s_lshl_b32 s44, s44, 7
	s_add_u32 s36, s36, s44
	s_add_u32 s36, s36, 0x2400000
	s_mov_b32 s37, 0x4000
	s_movk_i32 s44, 0x1600
	s_mov_b32 s99, 0x1000
.Lwc0_tj_2:
	s_load_dwordx2 s[2:3], s[0:1], s41
	s_add_u32 s66, s4, s36
	s_addc_u32 s67, s5, 0
	v_mad_u32_u24 v200, v203, s99, v204
	v_mad_u32_u24 v202, v205, s44, v206
	s_waitcnt lgkmcnt(0)
	s_add_u32 s38, s2, s38
	s_addc_u32 s39, s3, 0
	global_load_dword v154, v200, s[38:39]
	s_add_u32 s38, s38, s37
	s_addc_u32 s39, s39, 0
	global_load_dword v155, v200, s[38:39]
	s_add_u32 s38, s38, s37
	s_addc_u32 s39, s39, 0
	global_load_dword v156, v200, s[38:39]
	s_add_u32 s38, s38, s37
	s_addc_u32 s39, s39, 0
	global_load_dword v157, v200, s[38:39]
	s_add_u32 s38, s38, s37
	s_addc_u32 s39, s39, 0
	global_load_dword v158, v200, s[38:39]
	s_add_u32 s38, s38, s37
	s_addc_u32 s39, s39, 0
	global_load_dword v159, v200, s[38:39]
	s_add_u32 s38, s38, s37
	s_addc_u32 s39, s39, 0
	global_load_dword v160, v200, s[38:39]
	s_add_u32 s38, s38, s37
	s_addc_u32 s39, s39, 0
	global_load_dword v161, v200, s[38:39]
	s_add_u32 s38, s38, s37
	s_addc_u32 s39, s39, 0
	global_load_dword v162, v200, s[38:39]
	s_add_u32 s38, s38, s37
	s_addc_u32 s39, s39, 0
	global_load_dword v163, v200, s[38:39]
	s_add_u32 s38, s38, s37
	s_addc_u32 s39, s39, 0
	global_load_dword v164, v200, s[38:39]
	s_add_u32 s38, s38, s37
	s_addc_u32 s39, s39, 0
	global_load_dword v165, v200, s[38:39]
	s_add_u32 s38, s38, s37
	s_addc_u32 s39, s39, 0
	global_load_dword v166, v200, s[38:39]
	s_add_u32 s38, s38, s37
	s_addc_u32 s39, s39, 0
	global_load_dword v167, v200, s[38:39]
	s_add_u32 s38, s38, s37
	s_addc_u32 s39, s39, 0
	global_load_dword v168, v200, s[38:39]
	s_add_u32 s38, s38, s37
	s_addc_u32 s39, s39, 0
	global_load_dword v169, v200, s[38:39]
	s_waitcnt vmcnt(16)
	ds_write_b32 v194, v138 offset:0
	ds_write_b32 v194, v139 offset:1040
	ds_write_b32 v194, v140 offset:2080
	ds_write_b32 v194, v141 offset:3120
	ds_write_b32 v194, v142 offset:4160
	ds_write_b32 v194, v143 offset:5200
	ds_write_b32 v194, v144 offset:6240
	ds_write_b32 v194, v145 offset:7280
	ds_write_b32 v194, v146 offset:8320
	ds_write_b32 v194, v147 offset:9360
	ds_write_b32 v194, v148 offset:10400
	ds_write_b32 v194, v149 offset:11440
	ds_write_b32 v194, v150 offset:12480
	ds_write_b32 v194, v151 offset:13520
	ds_write_b32 v194, v152 offset:14560
	ds_write_b32 v194, v153 offset:15600
	s_waitcnt lgkmcnt(0)
	s_barrier
	ds_read2_b32 v[170:171], v195 offset1:65
	ds_read2_b32 v[172:173], v195 offset0:130 offset1:195
	ds_read2_b32 v[174:175], v196 offset0:4 offset1:69
	ds_read2_b32 v[176:177], v196 offset0:134 offset1:199
	ds_read2_b32 v[178:179], v197 offset1:65
	ds_read2_b32 v[180:181], v197 offset0:130 offset1:195
	ds_read2_b32 v[182:183], v198 offset0:4 offset1:69
	ds_read2_b32 v[184:185], v198 offset0:134 offset1:199
	s_add_u32 s96, s52, s32
	s_addc_u32 s97, s53, 0
	s_waitcnt lgkmcnt(0)
	s_barrier
	v_cvt_pk_bf16_f32 v186, v170, v171
	v_cvt_pk_bf16_f32 v187, v172, v173
	v_cvt_pk_bf16_f32 v188, v174, v175
	v_cvt_pk_bf16_f32 v189, v176, v177
	v_cvt_pk_bf16_f32 v190, v178, v179
	v_cvt_pk_bf16_f32 v191, v180, v181
	v_cvt_pk_bf16_f32 v192, v182, v183
	v_cvt_pk_bf16_f32 v193, v184, v185
	global_store_dwordx4 v201, v[186:189], s[52:53]
	global_store_dwordx4 v201, v[190:193], s[96:97]
	v_readlane_b32 s41, v207, 0
	v_readlane_b32 s44, v207, 1
	s_nop 0
	s_add_u32 s100, s100, s41
	s_cmp_ge_u32 s100, s44
	s_cbranch_scc1 .Lwc0_last1
	s_mov_b32 s101, s100
	s_cmpk_ge_u32 s101, 0x900
	s_cbranch_scc1 .Lwc0_t3_3
	s_cmpk_ge_u32 s101, 0x380
	s_cbranch_scc1 .Lwc0_t2_3
	s_cmpk_ge_u32 s101, 0x280
	s_cbranch_scc1 .Lwc0_t1_3
	s_movk_i32 s41, 0x78
	s_sub_u32 s99, s101, 0
	s_mul_i32 s44, s99, 0x66667
	s_lshr_b32 s44, s44, 24
	s_mul_i32 s36, s44, 40
	s_sub_u32 s99, s99, s36
	s_mul_i32 s38, s44, 0xa0000
	s_lshl_b32 s36, s99, 8
	s_add_u32 s38, s38, s36
	s_add_u32 s38, s38, 0x0
	s_lshl_b32 s36, s99, 6
	s_mov_b32 s32, 0x10000
	s_mul_i32 s36, s36, 0x800
	s_lshl_b32 s44, s44, 7
	s_add_u32 s36, s36, s44
	s_add_u32 s36, s36, 0x0
	s_mov_b32 s37, 0xa000
	s_movk_i32 s44, 0x800
	s_mov_b32 s99, 0x2800
	s_branch .Lwc0_tj_3

.Lwc0_tj_3:
	s_load_dwordx2 s[2:3], s[0:1], s41
	s_add_u32 s52, s4, s36
	s_addc_u32 s53, s5, 0
	v_mad_u32_u24 v199, v203, s99, v204
	v_mad_u32_u24 v201, v205, s44, v206
	s_waitcnt lgkmcnt(0)
	s_add_u32 s38, s2, s38
	s_addc_u32 s39, s3, 0
	global_load_dword v138, v199, s[38:39]
	s_add_u32 s38, s38, s37
	s_addc_u32 s39, s39, 0
	global_load_dword v139, v199, s[38:39]
	s_add_u32 s38, s38, s37
	s_addc_u32 s39, s39, 0
	global_load_dword v140, v199, s[38:39]
	s_add_u32 s38, s38, s37
	s_addc_u32 s39, s39, 0
	global_load_dword v141, v199, s[38:39]
	s_add_u32 s38, s38, s37
	s_addc_u32 s39, s39, 0
	global_load_dword v142, v199, s[38:39]
	s_add_u32 s38, s38, s37
	s_addc_u32 s39, s39, 0
	global_load_dword v143, v199, s[38:39]
	s_add_u32 s38, s38, s37
	s_addc_u32 s39, s39, 0
	global_load_dword v144, v199, s[38:39]
	s_add_u32 s38, s38, s37
	s_addc_u32 s39, s39, 0
	global_load_dword v145, v199, s[38:39]
	s_add_u32 s38, s38, s37
	s_addc_u32 s39, s39, 0
	global_load_dword v146, v199, s[38:39]
	s_add_u32 s38, s38, s37
	s_addc_u32 s39, s39, 0
	global_load_dword v147, v199, s[38:39]
	s_add_u32 s38, s38, s37
	s_addc_u32 s39, s39, 0
	global_load_dword v148, v199, s[38:39]
	s_add_u32 s38, s38, s37
	s_addc_u32 s39, s39, 0
	global_load_dword v149, v199, s[38:39]
	s_add_u32 s38, s38, s37
	s_addc_u32 s39, s39, 0
	global_load_dword v150, v199, s[38:39]
	s_add_u32 s38, s38, s37
	s_addc_u32 s39, s39, 0
	global_load_dword v151, v199, s[38:39]
	s_add_u32 s38, s38, s37
	s_addc_u32 s39, s39, 0
	global_load_dword v152, v199, s[38:39]
	s_add_u32 s38, s38, s37
	s_addc_u32 s39, s39, 0
	global_load_dword v153, v199, s[38:39]
	s_waitcnt vmcnt(16)
	ds_write_b32 v194, v154 offset:0
	ds_write_b32 v194, v155 offset:1040
	ds_write_b32 v194, v156 offset:2080
	ds_write_b32 v194, v157 offset:3120
	ds_write_b32 v194, v158 offset:4160
	ds_write_b32 v194, v159 offset:5200
	ds_write_b32 v194, v160 offset:6240
	ds_write_b32 v194, v161 offset:7280
	ds_write_b32 v194, v162 offset:8320
	ds_write_b32 v194, v163 offset:9360
	ds_write_b32 v194, v164 offset:10400
	ds_write_b32 v194, v165 offset:11440
	ds_write_b32 v194, v166 offset:12480
	ds_write_b32 v194, v167 offset:13520
	ds_write_b32 v194, v168 offset:14560
	ds_write_b32 v194, v169 offset:15600
	s_waitcnt lgkmcnt(0)
	s_barrier
	ds_read2_b32 v[170:171], v195 offset1:65
	ds_read2_b32 v[172:173], v195 offset0:130 offset1:195
	ds_read2_b32 v[174:175], v196 offset0:4 offset1:69
	ds_read2_b32 v[176:177], v196 offset0:134 offset1:199
	ds_read2_b32 v[178:179], v197 offset1:65
	ds_read2_b32 v[180:181], v197 offset0:130 offset1:195
	ds_read2_b32 v[182:183], v198 offset0:4 offset1:69
	ds_read2_b32 v[184:185], v198 offset0:134 offset1:199
	s_add_u32 s96, s66, s35
	s_addc_u32 s97, s67, 0
	s_waitcnt lgkmcnt(0)
	s_barrier
	v_cvt_pk_bf16_f32 v186, v170, v171
	v_cvt_pk_bf16_f32 v187, v172, v173
	v_cvt_pk_bf16_f32 v188, v174, v175
	v_cvt_pk_bf16_f32 v189, v176, v177
	v_cvt_pk_bf16_f32 v190, v178, v179
	v_cvt_pk_bf16_f32 v191, v180, v181
	v_cvt_pk_bf16_f32 v192, v182, v183
	v_cvt_pk_bf16_f32 v193, v184, v185
	global_store_dwordx4 v202, v[186:189], s[66:67]
	global_store_dwordx4 v202, v[190:193], s[96:97]
	s_branch .Lwc0_loop
.Lwc0_last0:
	s_waitcnt vmcnt(0)
	ds_write_b32 v194, v138 offset:0
	ds_write_b32 v194, v139 offset:1040
	ds_write_b32 v194, v140 offset:2080
	ds_write_b32 v194, v141 offset:3120
	ds_write_b32 v194, v142 offset:4160
	ds_write_b32 v194, v143 offset:5200
	ds_write_b32 v194, v144 offset:6240
	ds_write_b32 v194, v145 offset:7280
	ds_write_b32 v194, v146 offset:8320
	ds_write_b32 v194, v147 offset:9360
	ds_write_b32 v194, v148 offset:10400
	ds_write_b32 v194, v149 offset:11440
	ds_write_b32 v194, v150 offset:12480
	ds_write_b32 v194, v151 offset:13520
	ds_write_b32 v194, v152 offset:14560
	ds_write_b32 v194, v153 offset:15600
	s_waitcnt lgkmcnt(0)
	s_barrier
	ds_read2_b32 v[170:171], v195 offset1:65
	ds_read2_b32 v[172:173], v195 offset0:130 offset1:195
	ds_read2_b32 v[174:175], v196 offset0:4 offset1:69
	ds_read2_b32 v[176:177], v196 offset0:134 offset1:199
	ds_read2_b32 v[178:179], v197 offset1:65
	ds_read2_b32 v[180:181], v197 offset0:130 offset1:195
	ds_read2_b32 v[182:183], v198 offset0:4 offset1:69
	ds_read2_b32 v[184:185], v198 offset0:134 offset1:199
	s_add_u32 s96, s52, s32
	s_addc_u32 s97, s53, 0
	s_waitcnt lgkmcnt(0)
	s_barrier
	v_cvt_pk_bf16_f32 v186, v170, v171
	v_cvt_pk_bf16_f32 v187, v172, v173
	v_cvt_pk_bf16_f32 v188, v174, v175
	v_cvt_pk_bf16_f32 v189, v176, v177
	v_cvt_pk_bf16_f32 v190, v178, v179
	v_cvt_pk_bf16_f32 v191, v180, v181
	v_cvt_pk_bf16_f32 v192, v182, v183
	v_cvt_pk_bf16_f32 v193, v184, v185
	global_store_dwordx4 v201, v[186:189], s[52:53]
	global_store_dwordx4 v201, v[190:193], s[96:97]
	s_branch .Lwc0_done
.Lwc0_last1:
	s_waitcnt vmcnt(0)
	ds_write_b32 v194, v154 offset:0
	ds_write_b32 v194, v155 offset:1040
	ds_write_b32 v194, v156 offset:2080
	ds_write_b32 v194, v157 offset:3120
	ds_write_b32 v194, v158 offset:4160
	ds_write_b32 v194, v159 offset:5200
	ds_write_b32 v194, v160 offset:6240
	ds_write_b32 v194, v161 offset:7280
	ds_write_b32 v194, v162 offset:8320
	ds_write_b32 v194, v163 offset:9360
	ds_write_b32 v194, v164 offset:10400
	ds_write_b32 v194, v165 offset:11440
	ds_write_b32 v194, v166 offset:12480
	ds_write_b32 v194, v167 offset:13520
	ds_write_b32 v194, v168 offset:14560
	ds_write_b32 v194, v169 offset:15600
	s_waitcnt lgkmcnt(0)
	s_barrier
	ds_read2_b32 v[170:171], v195 offset1:65
	ds_read2_b32 v[172:173], v195 offset0:130 offset1:195
	ds_read2_b32 v[174:175], v196 offset0:4 offset1:69
	ds_read2_b32 v[176:177], v196 offset0:134 offset1:199
	ds_read2_b32 v[178:179], v197 offset1:65
	ds_read2_b32 v[180:181], v197 offset0:130 offset1:195
	ds_read2_b32 v[182:183], v198 offset0:4 offset1:69
	ds_read2_b32 v[184:185], v198 offset0:134 offset1:199
	s_add_u32 s96, s66, s35
	s_addc_u32 s97, s67, 0
	s_waitcnt lgkmcnt(0)
	s_barrier
	v_cvt_pk_bf16_f32 v186, v170, v171
	v_cvt_pk_bf16_f32 v187, v172, v173
	v_cvt_pk_bf16_f32 v188, v174, v175
	v_cvt_pk_bf16_f32 v189, v176, v177
	v_cvt_pk_bf16_f32 v190, v178, v179
	v_cvt_pk_bf16_f32 v191, v180, v181
	v_cvt_pk_bf16_f32 v192, v182, v183
	v_cvt_pk_bf16_f32 v193, v184, v185
	global_store_dwordx4 v202, v[186:189], s[66:67]
	global_store_dwordx4 v202, v[190:193], s[96:97]
.Lwc0_done:
	s_waitcnt vmcnt(0) lgkmcnt(0)
	s_barrier
	s_waitcnt lgkmcnt(0)
	v_writelane_b32 v242, s80, 60
	s_cmp_gt_i32 s60, -1
	s_nop 0
	v_writelane_b32 v241, s84, 0
	v_writelane_b32 v241, s85, 1
	v_writelane_b32 v241, s86, 2
	v_writelane_b32 v241, s87, 3
	v_writelane_b32 v241, s88, 4
	v_writelane_b32 v241, s89, 5
	v_writelane_b32 v242, s81, 61
	v_writelane_b32 v241, s90, 6
	v_writelane_b32 v242, s82, 62
	v_writelane_b32 v241, s91, 7
	v_writelane_b32 v242, s83, 63
	v_writelane_b32 v241, s92, 8
	v_writelane_b32 v241, s93, 9
	v_readlane_b32 s46, v242, 58
	v_writelane_b32 v241, s94, 10
	v_readlane_b32 s47, v242, 59
	v_writelane_b32 v241, s95, 11
	s_cbranch_scc1 .LBB0_161
	v_lshrrev_b32_e32 v1, 20, v0
	v_lshrrev_b32_e32 v0, 10, v0
	v_or_b32_e32 v0, v0, v1
	s_movk_i32 s0, 0x3ff
	v_and_or_b32 v0, v0, s0, v137
	v_cmp_eq_u32_e32 vcc, 0, v0
	s_barrier
	s_and_saveexec_b64 s[0:1], vcc
	s_cbranch_execz .LBB0_160
	v_readlane_b32 s2, v242, 42
	v_readlane_b32 s3, v242, 43
	buffer_wbl2 sc1
	s_waitcnt vmcnt(0)
	s_load_dwordx2 s[2:3], s[2:3], 0x58
	v_mov_b32_e32 v2, 0
	s_mov_b64 s[4:5], exec
	v_mbcnt_lo_u32_b32 v1, s4, 0
	v_mbcnt_hi_u32_b32 v1, s5, v1
	s_waitcnt lgkmcnt(0)
	global_load_dword v0, v2, s[2:3] offset:40
	v_cmp_eq_u32_e32 vcc, 0, v1
	s_and_saveexec_b64 s[6:7], vcc
	s_cbranch_execz .LBB0_153
	s_bcnt1_i32_b64 s4, s[4:5]
	v_mov_b32_e32 v3, s4
	global_atomic_add v3, v2, v3, s[2:3] offset:32 sc0

.LBB0_192:
	s_or_b64 exec, exec, s[6:7]
	s_waitcnt vmcnt(0)
	s_nop 0
	s_waitcnt vmcnt(0)

.LBB0_210:
	s_or_b64 exec, exec, s[4:5]
	s_mov_b64 s[4:5], exec
	v_mbcnt_lo_u32_b32 v0, s4, 0
	v_mbcnt_hi_u32_b32 v0, s5, v0
	v_cmp_eq_u32_e32 vcc, 0, v0
	s_waitcnt vmcnt(0)
	s_nop 0
	s_and_saveexec_b64 s[6:7], vcc
	s_cbranch_execz .LBB0_212
	s_bcnt1_i32_b64 s4, s[4:5]
	v_mov_b32_e32 v0, 0x2000
	v_mov_b32_e32 v1, s4
	s_nop 0

.LBB0_213:
	s_or_b64 exec, exec, s[0:1]
	v_readlane_b32 s2, v242, 42
	s_waitcnt lgkmcnt(0)
	v_mov_b32_e32 v0, v137
	v_readlane_b32 s3, v242, 43
	v_readfirstlane_b32 s99, v137
	s_cmp_lg_u32 s99, 64
	s_cbranch_scc1 .Lxbi0_skip
	buffer_inv sc1
	s_waitcnt vmcnt(0)
.Lxbi0_skip:
	s_barrier
	s_load_dword s0, s[2:3], 0x10
	s_load_dword s45, s[2:3], 0x0
	v_ashrrev_i32_e32 v2, 6, v0
	s_waitcnt lgkmcnt(0)
	s_lshr_b32 s0, s0, 16
	s_cmp_lg_u32 s0, 0
	s_cselect_b64 s[0:1], -1, 0
	s_cmp_lg_u64 s[0:1], 0
	s_addc_u32 s50, s45, 0
	s_lshl_b32 s51, s50, 2
	s_abs_i32 s0, s51
	v_cvt_f32_u32_e32 v1, s0
	s_sub_i32 s3, 0, s0
	s_add_i32 s1, s51, 0x27ff
	s_xor_b32 s2, s1, s51
	v_rcp_iflag_f32_e32 v1, v1
	s_abs_i32 s1, s1
	s_ashr_i32 s2, s2, 31
	v_mul_f32_e32 v1, 0x4f7ffffe, v1
	v_cvt_u32_f32_e32 v1, v1
	s_nop 0
	v_readfirstlane_b32 s4, v1
	s_mul_i32 s3, s3, s4
	s_mul_hi_u32 s3, s4, s3
	s_add_i32 s4, s4, s3
	s_mul_hi_u32 s3, s1, s4
	s_mul_i32 s4, s3, s0
	s_sub_i32 s1, s1, s4
	s_add_i32 s5, s3, 1
	s_sub_i32 s4, s1, s0
	s_cmp_ge_u32 s1, s0
	s_cselect_b32 s3, s5, s3
	s_cselect_b32 s1, s4, s1
	s_add_i32 s4, s3, 1
	s_cmp_ge_u32 s1, s0
	s_cselect_b32 s0, s4, s3
	s_xor_b32 s0, s0, s2
	s_sub_i32 s1, s0, s2
	v_readlane_b32 s0, v242, 0
	v_writelane_b32 v241, s1, 12
	s_nop 0
	v_lshl_add_u32 v1, s0, 2, v2
	v_mul_lo_u32 v16, v1, s1
	v_add_u32_e32 v1, s1, v16
	v_min_i32_e32 v40, 0x2800, v1
	v_cmp_lt_i32_e32 vcc, v16, v40
	s_and_saveexec_b64 s[0:1], vcc
	s_cbranch_execz .LBB0_218
	v_readfirstlane_b32 s6, v16
	v_readfirstlane_b32 s7, v40
	v_readlane_b32 s36, v242, 42
	v_readlane_b32 s37, v242, 43
	v_readlane_b32 s14, v242, 1
	v_readlane_b32 s15, v242, 2
	v_readlane_b32 s20, v242, 3
	v_readlane_b32 s21, v242, 4
	v_and_b32_e32 v236, 63, v137
	v_lshlrev_b32_e32 v237, 3, v236
	v_lshlrev_b32_e32 v236, 4, v236
	v_mov_b32_e32 v238, 0x358637bd
	s_sub_u32 s36, s36, 0x118
	s_subb_u32 s37, s37, 0
	s_load_dwordx2 s[12:13], s[36:37], 0x58
	s_load_dwordx4 s[16:19], s[36:37], 0x0
	s_add_u32 s22, s20, 0x2f90000
	s_addc_u32 s23, s21, 0
	s_mov_b32 s8, -1
	s_waitcnt lgkmcnt(0)
	s_cmp_lt_u32 s6, 0x2000
	s_cselect_b32 s24, s16, s18
	s_cselect_b32 s25, s17, s19
	s_cselect_b32 s9, 0, 0x2000
	s_sub_u32 s9, s6, s9
	s_lshl_b32 s9, s9, 12
	s_add_u32 s24, s24, s9
	s_addc_u32 s25, s25, 0
	global_load_dwordx4 v[188:191], v236, s[24:25] offset:0
	global_load_dwordx4 v[192:195], v236, s[24:25] offset:1024
	global_load_dwordx4 v[196:199], v236, s[24:25] offset:2048
	global_load_dwordx4 v[200:203], v236, s[24:25] offset:3072

.LBB0_378:
	s_cmp_lg_u32 s50, s33
	s_mov_b64 s[2:3], -1
	s_cbranch_scc0 .LBB0_381
	s_sub_i32 s2, s60, s33
	s_cmpk_lt_i32 s2, 0xbe4
	s_cselect_b64 s[2:3], -1, 0
	s_and_b64 s[0:1], s[0:1], s[2:3]
	s_andn2_b64 vcc, exec, s[0:1]
	s_mov_b32 s8, s20
	s_mov_b32 s33, s19
	s_mov_b32 s34, s28
	s_cbranch_vccnz .LBB0_380
	s_sub_u32 s100, s60, 0x100
	s_movk_i32 s41, 0x100
	s_movk_i32 s44, 0xbc0
	v_writelane_b32 v207, s41, 0
	v_writelane_b32 v207, s44, 1
	s_waitcnt vmcnt(0) lgkmcnt(0)
	s_barrier
	v_readlane_b32 s0, v242, 42
	v_readlane_b32 s1, v242, 43
	v_readlane_b32 s4, v242, 3
	v_readlane_b32 s5, v242, 4
	v_lshrrev_b32_e32 v203, 6, v137
	v_and_b32_e32 v204, 63, v137
	s_sub_u32 s0, s0, 0x118
	s_subb_u32 s1, s1, 0
	v_lshrrev_b32_e32 v205, 3, v137
	v_and_b32_e32 v206, 7, v137
	v_mul_u32_u24_e32 v194, 65, v203
	v_mul_u32_u24_e32 v195, 0x208, v206
	v_add_u32_e32 v194, v194, v204
	v_add_u32_e32 v195, v195, v205
	v_lshlrev_b32_e32 v194, 2, v194
	v_lshlrev_b32_e32 v195, 2, v195
	v_lshlrev_b32_e32 v204, 2, v204
	v_lshlrev_b32_e32 v206, 4, v206
	v_add_u32_e32 v196, 0x400, v195
	v_add_u32_e32 v197, 0x80, v195
	v_add_u32_e32 v198, 0x480, v195
	v_readlane_b32 s41, v207, 1
	s_nop 0
	s_cmp_ge_u32 s100, s41
	s_cbranch_scc1 .Lwc1_done
	s_mov_b32 s101, s100
	s_cmpk_ge_u32 s101, 0x900
	s_cbranch_scc1 .Lwc1_t3_1
	s_cmpk_ge_u32 s101, 0x380
	s_cbranch_scc1 .Lwc1_t2_1
	s_cmpk_ge_u32 s101, 0x280
	s_cbranch_scc1 .Lwc1_t1_1
	s_movk_i32 s41, 0x78
	s_sub_u32 s99, s101, 0
	s_mul_i32 s44, s99, 0x66667
	s_lshr_b32 s44, s44, 24
	s_mul_i32 s36, s44, 40
	s_sub_u32 s99, s99, s36
	s_mul_i32 s38, s44, 0xa0000
	s_lshl_b32 s36, s99, 8
	s_add_u32 s38, s38, s36
	s_add_u32 s38, s38, 0xa00000
	s_lshl_b32 s36, s99, 6
	s_mov_b32 s32, 0x10000
	s_mul_i32 s36, s36, 0x800
	s_lshl_b32 s44, s44, 7
	s_add_u32 s36, s36, s44
	s_add_u32 s36, s36, 0x500000
	s_mov_b32 s37, 0xa000
	s_movk_i32 s44, 0x800
	s_mov_b32 s99, 0x2800
	s_branch .Lwc1_tj_1
.Lwc1_t1_1:
	s_movk_i32 s41, 0x80
	s_sub_u32 s99, s101, 640
	s_mul_i32 s44, s99, 0x100000
	s_lshr_b32 s44, s44, 24
	s_mul_i32 s36, s44, 16
	s_sub_u32 s99, s99, s36
	s_mul_i32 s38, s44, 0x40000
	s_lshl_b32 s36, s99, 8
	s_add_u32 s38, s38, s36
	s_add_u32 s38, s38, 0x400000
	s_lshl_b32 s36, s99, 6
	s_mov_b32 s32, 0x10000
	s_mul_i32 s36, s36, 0x800
	s_lshl_b32 s44, s44, 7
	s_add_u32 s36, s36, s44
	s_add_u32 s36, s36, 0xc00000
	s_mov_b32 s37, 0x4000
	s_movk_i32 s44, 0x800
	s_mov_b32 s99, 0x1000
	s_branch .Lwc1_tj_1
.Lwc1_t2_1:
	s_movk_i32 s41, 0xf0
	s_sub_u32 s99, s101, 896
	s_mul_i32 s44, s99, 0x2e8bb
	s_lshr_b32 s44, s44, 24
	s_mul_i32 s36, s44, 88
	s_sub_u32 s99, s99, s36
	s_mul_i32 s38, s44, 0x160000
	s_lshl_b32 s36, s99, 8
	s_add_u32 s38, s38, s36
	s_add_u32 s38, s38, 0x1600000
	s_cmpk_ge_u32 s99, 44
	s_cselect_b32 s36, 44, 0
	s_cselect_b32 s37, 32, 0
	s_sub_u32 s36, s99, s36
	s_lshl_b32 s36, s36, 7
	s_add_u32 s36, s36, s37
	s_mov_b32 s32, 0x20000
	s_mul_i32 s36, s36, 0x800
	s_lshl_b32 s44, s44, 7
	s_add_u32 s36, s36, s44
	s_add_u32 s36, s36, 0x1900000
	s_mov_b32 s37, 0x16000
	s_movk_i32 s44, 0x800
	s_mov_b32 s99, 0x5800
	s_branch .Lwc1_tj_1
.Lwc1_t3_1:
	s_movk_i32 s41, 0xf8
	s_sub_u32 s99, s101, 2304
	s_mul_i32 s44, s99, 0x100000
	s_lshr_b32 s44, s44, 24
	s_mul_i32 s36, s44, 16
	s_sub_u32 s99, s99, s36
	s_mul_i32 s38, s44, 0x40000
	s_lshl_b32 s36, s99, 8
	s_add_u32 s38, s38, s36
	s_add_u32 s38, s38, 0xb00000
	s_lshl_b32 s36, s99, 6
	s_mov_b32 s32, 0x2c000
	s_mul_i32 s36, s36, 0x1600
	s_lshl_b32 s44, s44, 7
	s_add_u32 s36, s36, s44
	s_add_u32 s36, s36, 0x2980000
	s_mov_b32 s37, 0x4000
	s_movk_i32 s44, 0x1600
	s_mov_b32 s99, 0x1000

.Lwc1_loop:
	v_readlane_b32 s41, v207, 0
	v_readlane_b32 s44, v207, 1
	s_nop 0
	s_add_u32 s100, s100, s41
	s_cmp_ge_u32 s100, s44
	s_cbranch_scc1 .Lwc1_last0
	s_mov_b32 s101, s100
	s_cmpk_ge_u32 s101, 0x900
	s_cbranch_scc1 .Lwc1_t3_2
	s_cmpk_ge_u32 s101, 0x380
	s_cbranch_scc1 .Lwc1_t2_2
	s_cmpk_ge_u32 s101, 0x280
	s_cbranch_scc1 .Lwc1_t1_2
	s_movk_i32 s41, 0x78
	s_sub_u32 s99, s101, 0
	s_mul_i32 s44, s99, 0x66667
	s_lshr_b32 s44, s44, 24
	s_mul_i32 s36, s44, 40
	s_sub_u32 s99, s99, s36
	s_mul_i32 s38, s44, 0xa0000
	s_lshl_b32 s36, s99, 8
	s_add_u32 s38, s38, s36
	s_add_u32 s38, s38, 0xa00000
	s_lshl_b32 s36, s99, 6
	s_mov_b32 s35, 0x10000
	s_mul_i32 s36, s36, 0x800
	s_lshl_b32 s44, s44, 7
	s_add_u32 s36, s36, s44
	s_add_u32 s36, s36, 0x500000
	s_mov_b32 s37, 0xa000
	s_movk_i32 s44, 0x800
	s_mov_b32 s99, 0x2800
	s_branch .Lwc1_tj_2
.Lwc1_t1_2:
	s_movk_i32 s41, 0x80
	s_sub_u32 s99, s101, 640
	s_mul_i32 s44, s99, 0x100000
	s_lshr_b32 s44, s44, 24
	s_mul_i32 s36, s44, 16
	s_sub_u32 s99, s99, s36
	s_mul_i32 s38, s44, 0x40000
	s_lshl_b32 s36, s99, 8
	s_add_u32 s38, s38, s36
	s_add_u32 s38, s38, 0x400000
	s_lshl_b32 s36, s99, 6
	s_mov_b32 s35, 0x10000
	s_mul_i32 s36, s36, 0x800
	s_lshl_b32 s44, s44, 7
	s_add_u32 s36, s36, s44
	s_add_u32 s36, s36, 0xc00000
	s_mov_b32 s37, 0x4000
	s_movk_i32 s44, 0x800
	s_mov_b32 s99, 0x1000
	s_branch .Lwc1_tj_2
.Lwc1_t2_2:
	s_movk_i32 s41, 0xf0
	s_sub_u32 s99, s101, 896
	s_mul_i32 s44, s99, 0x2e8bb
	s_lshr_b32 s44, s44, 24
	s_mul_i32 s36, s44, 88
	s_sub_u32 s99, s99, s36
	s_mul_i32 s38, s44, 0x160000
	s_lshl_b32 s36, s99, 8
	s_add_u32 s38, s38, s36
	s_add_u32 s38, s38, 0x1600000
	s_cmpk_ge_u32 s99, 44
	s_cselect_b32 s36, 44, 0
	s_cselect_b32 s37, 32, 0
	s_sub_u32 s36, s99, s36
	s_lshl_b32 s36, s36, 7
	s_add_u32 s36, s36, s37
	s_mov_b32 s35, 0x20000
	s_mul_i32 s36, s36, 0x800
	s_lshl_b32 s44, s44, 7
	s_add_u32 s36, s36, s44
	s_add_u32 s36, s36, 0x1900000
	s_mov_b32 s37, 0x16000
	s_movk_i32 s44, 0x800
	s_mov_b32 s99, 0x5800
	s_branch .Lwc1_tj_2
.Lwc1_t3_2:
	s_movk_i32 s41, 0xf8
	s_sub_u32 s99, s101, 2304
	s_mul_i32 s44, s99, 0x100000
	s_lshr_b32 s44, s44, 24
	s_mul_i32 s36, s44, 16
	s_sub_u32 s99, s99, s36
	s_mul_i32 s38, s44, 0x40000
	s_lshl_b32 s36, s99, 8
	s_add_u32 s38, s38, s36
	s_add_u32 s38, s38, 0xb00000
	s_lshl_b32 s36, s99, 6
	s_mov_b32 s35, 0x2c000
	s_mul_i32 s36, s36, 0x1600
	s_lshl_b32 s44, s44, 7
	s_add_u32 s36, s36, s44
	s_add_u32 s36, s36, 0x2980000
	s_mov_b32 s37, 0x4000
	s_movk_i32 s44, 0x1600
	s_mov_b32 s99, 0x1000
.Lwc1_tj_2:
	s_load_dwordx2 s[2:3], s[0:1], s41
	s_add_u32 s66, s4, s36
	s_addc_u32 s67, s5, 0
	v_mad_u32_u24 v200, v203, s99, v204
	v_mad_u32_u24 v202, v205, s44, v206
	s_waitcnt lgkmcnt(0)
	s_add_u32 s38, s2, s38
	s_addc_u32 s39, s3, 0
	global_load_dword v154, v200, s[38:39]
	s_add_u32 s38, s38, s37
	s_addc_u32 s39, s39, 0
	global_load_dword v155, v200, s[38:39]
	s_add_u32 s38, s38, s37
	s_addc_u32 s39, s39, 0
	global_load_dword v156, v200, s[38:39]
	s_add_u32 s38, s38, s37
	s_addc_u32 s39, s39, 0
	global_load_dword v157, v200, s[38:39]
	s_add_u32 s38, s38, s37
	s_addc_u32 s39, s39, 0
	global_load_dword v158, v200, s[38:39]
	s_add_u32 s38, s38, s37
	s_addc_u32 s39, s39, 0
	global_load_dword v159, v200, s[38:39]
	s_add_u32 s38, s38, s37
	s_addc_u32 s39, s39, 0
	global_load_dword v160, v200, s[38:39]
	s_add_u32 s38, s38, s37
	s_addc_u32 s39, s39, 0
	global_load_dword v161, v200, s[38:39]
	s_add_u32 s38, s38, s37
	s_addc_u32 s39, s39, 0
	global_load_dword v162, v200, s[38:39]
	s_add_u32 s38, s38, s37
	s_addc_u32 s39, s39, 0
	global_load_dword v163, v200, s[38:39]
	s_add_u32 s38, s38, s37
	s_addc_u32 s39, s39, 0
	global_load_dword v164, v200, s[38:39]
	s_add_u32 s38, s38, s37
	s_addc_u32 s39, s39, 0
	global_load_dword v165, v200, s[38:39]
	s_add_u32 s38, s38, s37
	s_addc_u32 s39, s39, 0
	global_load_dword v166, v200, s[38:39]
	s_add_u32 s38, s38, s37
	s_addc_u32 s39, s39, 0
	global_load_dword v167, v200, s[38:39]
	s_add_u32 s38, s38, s37
	s_addc_u32 s39, s39, 0
	global_load_dword v168, v200, s[38:39]
	s_add_u32 s38, s38, s37
	s_addc_u32 s39, s39, 0
	global_load_dword v169, v200, s[38:39]
	s_waitcnt vmcnt(16)
	ds_write_b32 v194, v138 offset:0
	ds_write_b32 v194, v139 offset:1040
	ds_write_b32 v194, v140 offset:2080
	ds_write_b32 v194, v141 offset:3120
	ds_write_b32 v194, v142 offset:4160
	ds_write_b32 v194, v143 offset:5200
	ds_write_b32 v194, v144 offset:6240
	ds_write_b32 v194, v145 offset:7280
	ds_write_b32 v194, v146 offset:8320
	ds_write_b32 v194, v147 offset:9360
	ds_write_b32 v194, v148 offset:10400
	ds_write_b32 v194, v149 offset:11440
	ds_write_b32 v194, v150 offset:12480
	ds_write_b32 v194, v151 offset:13520
	ds_write_b32 v194, v152 offset:14560
	ds_write_b32 v194, v153 offset:15600
	s_waitcnt lgkmcnt(0)
	s_barrier
	ds_read2_b32 v[170:171], v195 offset1:65
	ds_read2_b32 v[172:173], v195 offset0:130 offset1:195
	ds_read2_b32 v[174:175], v196 offset0:4 offset1:69
	ds_read2_b32 v[176:177], v196 offset0:134 offset1:199
	ds_read2_b32 v[178:179], v197 offset1:65
	ds_read2_b32 v[180:181], v197 offset0:130 offset1:195
	ds_read2_b32 v[182:183], v198 offset0:4 offset1:69
	ds_read2_b32 v[184:185], v198 offset0:134 offset1:199
	s_add_u32 s96, s52, s32
	s_addc_u32 s97, s53, 0
	s_waitcnt lgkmcnt(0)
	s_barrier
	v_cvt_pk_bf16_f32 v186, v170, v171
	v_cvt_pk_bf16_f32 v187, v172, v173
	v_cvt_pk_bf16_f32 v188, v174, v175
	v_cvt_pk_bf16_f32 v189, v176, v177
	v_cvt_pk_bf16_f32 v190, v178, v179
	v_cvt_pk_bf16_f32 v191, v180, v181
	v_cvt_pk_bf16_f32 v192, v182, v183
	v_cvt_pk_bf16_f32 v193, v184, v185
	global_store_dwordx4 v201, v[186:189], s[52:53]
	global_store_dwordx4 v201, v[190:193], s[96:97]
	v_readlane_b32 s41, v207, 0
	v_readlane_b32 s44, v207, 1
	s_nop 0
	s_add_u32 s100, s100, s41
	s_cmp_ge_u32 s100, s44
	s_cbranch_scc1 .Lwc1_last1
	s_mov_b32 s101, s100
	s_cmpk_ge_u32 s101, 0x900
	s_cbranch_scc1 .Lwc1_t3_3
	s_cmpk_ge_u32 s101, 0x380
	s_cbranch_scc1 .Lwc1_t2_3
	s_cmpk_ge_u32 s101, 0x280
	s_cbranch_scc1 .Lwc1_t1_3
	s_movk_i32 s41, 0x78
	s_sub_u32 s99, s101, 0
	s_mul_i32 s44, s99, 0x66667
	s_lshr_b32 s44, s44, 24
	s_mul_i32 s36, s44, 40
	s_sub_u32 s99, s99, s36
	s_mul_i32 s38, s44, 0xa0000
	s_lshl_b32 s36, s99, 8
	s_add_u32 s38, s38, s36
	s_add_u32 s38, s38, 0xa00000
	s_lshl_b32 s36, s99, 6
	s_mov_b32 s32, 0x10000
	s_mul_i32 s36, s36, 0x800
	s_lshl_b32 s44, s44, 7
	s_add_u32 s36, s36, s44
	s_add_u32 s36, s36, 0x500000
	s_mov_b32 s37, 0xa000
	s_movk_i32 s44, 0x800
	s_mov_b32 s99, 0x2800
	s_branch .Lwc1_tj_3

.Lwc1_done:
	s_waitcnt vmcnt(0) lgkmcnt(0)
	s_barrier
	s_branch .LBB0_396

.LBB0_396:
	s_add_i32 s2, s33, 0xffff0bd8
	s_cmpk_lt_u32 s2, 0xbc0
	s_cbranch_scc1 .LBB0_395
	s_cmpk_gt_i32 s2, 0x27f
	s_mov_b64 s[0:1], -1
	s_cbranch_scc0 .LBB0_426
	s_cmpk_gt_u32 s2, 0x37f
	s_cbranch_scc0 .LBB0_423
	s_cmpk_gt_u32 s2, 0x8ff
	s_cbranch_scc0 .LBB0_412
	s_cmpk_gt_u32 s2, 0xbbf
	s_cbranch_scc0 .LBB0_409
	s_cmpk_gt_u32 s2, 0xbcb
	s_cbranch_scc0 .LBB0_406
	s_cmpk_gt_u32 s2, 0xbd7
	s_cbranch_scc0 .LBB0_403
	s_and_b32 s0, s33, 0xffff
	s_cmp_gt_u32 s0, 5
	s_cselect_b32 s3, 64, 0
	s_add_i32 s1, s49, s34
	s_cmp_lt_u32 s0, 6
	s_mov_b32 s0, 0x36ca00
	s_cselect_b32 s0, s0, 0x76c880
	s_add_i32 s1, s1, s0
	s_and_b32 s4, s1, 0x3fffc0
	v_mov_b32_e32 v18, v137
	s_lshl_b32 s0, s4, 2
	v_readlane_b32 s1, v241, 21
	s_add_u32 s0, s1, s0
	v_ashrrev_i32_e32 v19, 6, v18
	v_readlane_b32 s1, v241, 22
	v_lshlrev_b32_e32 v0, 2, v18
	s_addc_u32 s1, s1, 0
	v_and_b32_e32 v94, 0xfc, v0
	v_add_u32_e32 v20, s3, v19
	v_lshl_add_u64 v[0:1], s[0:1], 0, v[94:95]
	v_add_u32_e32 v4, 4, v20
	v_add_u32_e32 v6, 8, v20
	v_add_u32_e32 v8, 12, v20
	v_add_u32_e32 v10, 16, v20
	v_add_u32_e32 v12, 20, v20
	v_add_u32_e32 v14, 24, v20
	v_add_u32_e32 v16, 28, v20
	v_mad_i64_i32 v[2:3], s[0:1], v20, s80, v[0:1]
	v_mad_i64_i32 v[4:5], s[0:1], v4, s80, v[0:1]
	v_mad_i64_i32 v[6:7], s[0:1], v6, s80, v[0:1]
	v_mad_i64_i32 v[8:9], s[0:1], v8, s80, v[0:1]
	v_mad_i64_i32 v[10:11], s[0:1], v10, s80, v[0:1]
	v_mad_i64_i32 v[12:13], s[0:1], v12, s80, v[0:1]
	v_mad_i64_i32 v[14:15], s[0:1], v14, s80, v[0:1]
	v_mad_i64_i32 v[16:17], s[0:1], v16, s80, v[0:1]
	global_load_dword v21, v[2:3], off
	global_load_dword v22, v[4:5], off
	global_load_dword v23, v[6:7], off
	global_load_dword v24, v[8:9], off
	global_load_dword v25, v[10:11], off
	global_load_dword v26, v[12:13], off
	global_load_dword v27, v[14:15], off
	s_nop 0
	global_load_dword v16, v[16:17], off
	v_add_u32_e32 v2, 32, v20
	v_add_u32_e32 v4, 36, v20
	v_add_u32_e32 v6, 40, v20
	v_add_u32_e32 v8, 44, v20
	v_add_u32_e32 v10, 48, v20
	v_add_u32_e32 v12, 52, v20
	v_add_u32_e32 v14, 56, v20
	v_add_u32_e32 v17, 60, v20
	v_mad_i64_i32 v[2:3], s[0:1], v2, s80, v[0:1]
	v_mad_i64_i32 v[4:5], s[0:1], v4, s80, v[0:1]
	v_mad_i64_i32 v[6:7], s[0:1], v6, s80, v[0:1]
	v_mad_i64_i32 v[8:9], s[0:1], v8, s80, v[0:1]
	v_mad_i64_i32 v[10:11], s[0:1], v10, s80, v[0:1]
	v_mad_i64_i32 v[12:13], s[0:1], v12, s80, v[0:1]
	v_mad_i64_i32 v[14:15], s[0:1], v14, s80, v[0:1]
	v_mad_i64_i32 v[0:1], s[0:1], v17, s80, v[0:1]
	global_load_dword v2, v[2:3], off
	s_nop 0
	global_load_dword v3, v[4:5], off
	s_nop 0
	global_load_dword v4, v[6:7], off
	global_load_dword v5, v[8:9], off
	s_nop 0
	global_load_dword v6, v[10:11], off
	global_load_dword v7, v[12:13], off
	global_load_dword v8, v[14:15], off
	s_nop 0
	global_load_dword v0, v[0:1], off
	v_mul_lo_u32 v1, v19, s81
	v_add3_u32 v1, 0, v94, v1
	v_ashrrev_i32_e32 v11, 3, v18
	s_lshl_b32 s0, s3, 1
	v_readlane_b32 s1, v241, 23
	s_add_u32 s0, s1, s0
	v_readlane_b32 s1, v241, 24
	s_addc_u32 s1, s1, 0
	s_waitcnt vmcnt(15)
	ds_write_b32 v1, v21
	s_waitcnt vmcnt(14)
	ds_write_b32 v1, v22 offset:1040
	s_waitcnt vmcnt(13)
	ds_write_b32 v1, v23 offset:2080
	s_waitcnt vmcnt(12)
	ds_write_b32 v1, v24 offset:3120
	s_waitcnt vmcnt(11)
	ds_write_b32 v1, v25 offset:4160
	s_waitcnt vmcnt(10)
	ds_write_b32 v1, v26 offset:5200
	s_waitcnt vmcnt(9)
	ds_write_b32 v1, v27 offset:6240
	s_waitcnt vmcnt(8)
	ds_write_b32 v1, v16 offset:7280
	s_waitcnt vmcnt(7)
	ds_write_b32 v1, v2 offset:8320
	s_waitcnt vmcnt(6)
	ds_write_b32 v1, v3 offset:9360
	s_waitcnt vmcnt(5)
	ds_write_b32 v1, v4 offset:10400
	s_waitcnt vmcnt(4)
	ds_write_b32 v1, v5 offset:11440
	s_waitcnt vmcnt(3)
	ds_write_b32 v1, v6 offset:12480
	s_waitcnt vmcnt(2)
	ds_write_b32 v1, v7 offset:13520
	s_waitcnt vmcnt(1)
	ds_write_b32 v1, v8 offset:14560
	s_waitcnt vmcnt(0)
	ds_write_b32 v1, v0 offset:15600
	v_lshlrev_b32_e32 v0, 3, v18
	v_and_b32_e32 v0, 56, v0
	v_mad_u32_u24 v10, v0, s81, 0
	v_lshl_add_u32 v4, v11, 2, v10
	s_waitcnt lgkmcnt(0)
	s_barrier
	v_lshlrev_b32_e32 v94, 1, v0
	ds_read2_b32 v[0:1], v4 offset1:65
	ds_read2_b32 v[2:3], v4 offset0:130 offset1:195
	v_add_u32_e32 v6, 0x400, v4
	ds_read2_b32 v[4:5], v6 offset0:4 offset1:69
	ds_read2_b32 v[6:7], v6 offset0:134 offset1:199
	v_lshl_add_u64 v[8:9], s[0:1], 0, v[94:95]
	s_waitcnt lgkmcnt(3)
	v_cvt_pk_bf16_f32 v0, v0, v1
	s_waitcnt lgkmcnt(2)
	v_cvt_pk_bf16_f32 v1, v2, v3
	s_waitcnt lgkmcnt(1)
	v_cvt_pk_bf16_f32 v2, v4, v5
	v_add_u32_e32 v4, s4, v11
	v_ashrrev_i32_e32 v5, 31, v4
	v_lshlrev_b64 v[4:5], 8, v[4:5]
	s_waitcnt lgkmcnt(0)
	v_cvt_pk_bf16_f32 v3, v6, v7
	v_lshl_add_u64 v[4:5], v[8:9], 0, v[4:5]
	global_store_dwordx4 v[4:5], v[0:3], off
	s_mov_b64 s[0:1], 0
	s_nop 0
	v_add_u32_e32 v0, 0x100, v18
	v_ashrrev_i32_e32 v2, 3, v0
	v_lshl_add_u32 v3, v2, 2, v10
	v_add_u32_e32 v4, 0x400, v3
	ds_read2_b32 v[0:1], v4 offset0:134 offset1:199
	ds_read2_b32 v[4:5], v4 offset0:4 offset1:69
	ds_read2_b32 v[6:7], v3 offset0:130 offset1:195
	ds_read2_b32 v[10:11], v3 offset1:65
	v_add_u32_e32 v12, s4, v2
	v_ashrrev_i32_e32 v13, 31, v12
	s_waitcnt lgkmcnt(2)
	v_cvt_pk_bf16_f32 v2, v4, v5
	v_lshlrev_b64 v[4:5], 8, v[12:13]
	v_cvt_pk_bf16_f32 v3, v0, v1
	s_waitcnt lgkmcnt(1)
	v_cvt_pk_bf16_f32 v1, v6, v7
	s_waitcnt lgkmcnt(0)
	v_cvt_pk_bf16_f32 v0, v10, v11
	v_lshl_add_u64 v[4:5], v[8:9], 0, v[4:5]
	global_store_dwordx4 v[4:5], v[0:3], off
	s_barrier
